# v70 + software-pipelined global loads in the meta-row mini-GEMM K loops and the gz projection loop (all loads of a K sweep in flight instead of one round trip per step)
# speedup vs baseline: 1.0073x; 1.0073x over previous
.LBB0_163:
	s_andn2_b64 vcc, exec, s[36:37]
	s_cbranch_vccnz .LBB0_171
	s_ashr_i32 s36, s2, 6
	v_mov_b32_e32 v3, 0
	s_cmp_gt_i32 s36, 31
	v_and_b32_e32 v11, 15, v10
	v_mov_b32_e32 v2, v3
	v_mov_b32_e32 v1, v3
	v_mov_b32_e32 v0, v3
	v_mov_b32_e32 v7, v3
	v_mov_b32_e32 v6, v3
	v_mov_b32_e32 v5, v3
	v_mov_b32_e32 v4, v3
	s_cbranch_scc1 .LBB0_167
	s_lshl_b32 s28, s36, 5
	s_ashr_i32 s29, s28, 31
	s_add_i32 s37, s36, -8
	s_lshl_b64 s[28:29], s[28:29], 1
	v_and_b32_e32 v0, 48, v10
	s_add_u32 s28, s66, s28
	v_lshl_or_b32 v142, v11, 11, v0
	s_addc_u32 s29, s67, s29
	v_mov_b32_e32 v0, 0
	v_lshl_add_u64 v[8:9], s[28:29], 0, v[142:143]
	v_mov_b32_e32 v1, v0
	v_mov_b32_e32 v2, v0
	v_mov_b32_e32 v3, v0
	v_mov_b32_e32 v4, v0
	v_mov_b32_e32 v5, v0
	v_mov_b32_e32 v6, v0
	v_mov_b32_e32 v7, v0
	s_nop 1
	v_lshl_add_u64 v[28:29], v[8:9], 0, s[8:9]
	v_lshl_add_u64 v[30:31], v[8:9], 0, s[6:7]
	v_add_co_u32_e32 v32, vcc, 0x9280000, v8
	s_nop 1
	v_addc_co_u32_e32 v33, vcc, 0, v9, vcc
	global_load_dwordx4 v[36:39], v[32:33], off
	global_load_dwordx4 v[40:43], v[28:29], off
	global_load_dwordx4 v[44:47], v[30:31], off
	global_load_dwordx4 v[48:51], v[32:33], off offset:512
	global_load_dwordx4 v[52:55], v[28:29], off offset:512
	global_load_dwordx4 v[56:59], v[30:31], off offset:512
	global_load_dwordx4 v[60:63], v[32:33], off offset:1024
	global_load_dwordx4 v[64:67], v[28:29], off offset:1024
	global_load_dwordx4 v[68:71], v[30:31], off offset:1024
	global_load_dwordx4 v[72:75], v[32:33], off offset:1536
	global_load_dwordx4 v[76:79], v[28:29], off offset:1536
	global_load_dwordx4 v[80:83], v[30:31], off offset:1536
	s_waitcnt vmcnt(9)
	v_mfma_f32_16x16x32_bf16 v[4:7], v[40:43], v[36:39], v[4:7]
	v_mfma_f32_16x16x32_bf16 v[0:3], v[44:47], v[36:39], v[0:3]
	s_waitcnt vmcnt(6)
	v_mfma_f32_16x16x32_bf16 v[4:7], v[52:55], v[48:51], v[4:7]
	v_mfma_f32_16x16x32_bf16 v[0:3], v[56:59], v[48:51], v[0:3]
	s_waitcnt vmcnt(3)
	v_mfma_f32_16x16x32_bf16 v[4:7], v[64:67], v[60:63], v[4:7]
	v_mfma_f32_16x16x32_bf16 v[0:3], v[68:71], v[60:63], v[0:3]
	s_waitcnt vmcnt(0)
	v_mfma_f32_16x16x32_bf16 v[4:7], v[76:79], v[72:75], v[4:7]
	v_mfma_f32_16x16x32_bf16 v[0:3], v[80:83], v[72:75], v[0:3]
	s_nop 7

.LBB0_242:
	s_andn2_b64 vcc, exec, s[36:37]
	s_cbranch_vccnz .LBB0_257
	s_ashr_i32 s36, s2, 6
	v_mov_b32_e32 v3, 0
	v_and_b32_e32 v22, 15, v12
	s_cmpk_gt_i32 s36, 0x57
	v_mov_b32_e32 v2, v3
	v_mov_b32_e32 v1, v3
	v_mov_b32_e32 v0, v3
	v_mov_b32_e32 v7, v3
	v_mov_b32_e32 v6, v3
	v_mov_b32_e32 v5, v3
	v_mov_b32_e32 v4, v3
	s_cbranch_scc1 .LBB0_246
	s_lshl_b32 s28, s36, 5
	s_ashr_i32 s29, s28, 31
	v_mul_u32_u24_e32 v2, 0xb00, v22
	s_lshl_b64 s[28:29], s[28:29], 1
	v_and_or_b32 v0, v12, 48, s28
	v_mov_b32_e32 v1, s29
	v_lshlrev_b32_e32 v142, 1, v2
	v_readlane_b32 s4, v250, 22
	v_lshl_add_u64 v[0:1], v[0:1], 0, v[142:143]
	v_readlane_b32 s5, v250, 23
	s_add_i32 s37, s36, -8
	s_nop 0
	v_lshl_add_u64 v[8:9], s[4:5], 0, v[0:1]
	v_mov_b32_e32 v0, 0
	v_mov_b32_e32 v1, v0
	v_mov_b32_e32 v2, v0
	v_mov_b32_e32 v3, v0
	v_mov_b32_e32 v4, v0
	v_mov_b32_e32 v5, v0
	v_mov_b32_e32 v6, v0
	v_mov_b32_e32 v7, v0
	s_nop 1
	v_lshl_add_u64 v[28:29], v[8:9], 0, s[6:7]
	v_add_co_u32_e32 v30, vcc, 0xee6c0000, v28
	s_nop 1
	v_addc_co_u32_e32 v31, vcc, -1, v29, vcc
	v_add_co_u32_e32 v32, vcc, 0xee6d6000, v28
	s_nop 1
	v_addc_co_u32_e32 v33, vcc, -1, v29, vcc
	s_mov_b64 s[28:29], 0xa00
	v_lshl_add_u64 v[34:35], v[8:9], 0, s[28:29]
	global_load_dwordx4 v[36:39], v[30:31], off offset:-2048
	global_load_dwordx4 v[40:43], v[32:33], off offset:-2048
	global_load_dwordx4 v[44:47], v[34:35], off offset:-2560
	global_load_dwordx4 v[48:51], v[30:31], off offset:-1536
	global_load_dwordx4 v[52:55], v[32:33], off offset:-1536
	global_load_dwordx4 v[56:59], v[34:35], off offset:-2048
	global_load_dwordx4 v[60:63], v[30:31], off offset:-1024
	global_load_dwordx4 v[64:67], v[32:33], off offset:-1024
	global_load_dwordx4 v[68:71], v[34:35], off offset:-1536
	global_load_dwordx4 v[72:75], v[30:31], off offset:-512
	global_load_dwordx4 v[76:79], v[32:33], off offset:-512
	global_load_dwordx4 v[80:83], v[34:35], off offset:-1024
	global_load_dwordx4 v[84:87], v[30:31], off
	global_load_dwordx4 v[88:91], v[32:33], off
	global_load_dwordx4 v[92:95], v[34:35], off offset:-512
	global_load_dwordx4 v[96:99], v[30:31], off offset:512
	global_load_dwordx4 v[100:103], v[32:33], off offset:512
	global_load_dwordx4 v[104:107], v[34:35], off
	global_load_dwordx4 v[108:111], v[30:31], off offset:1024
	global_load_dwordx4 v[112:115], v[32:33], off offset:1024
	global_load_dwordx4 v[116:119], v[34:35], off offset:512
	global_load_dwordx4 v[120:123], v[30:31], off offset:1536
	global_load_dwordx4 v[124:127], v[32:33], off offset:1536
	global_load_dwordx4 v[128:131], v[34:35], off offset:1024
	s_waitcnt vmcnt(21)
	v_mfma_f32_16x16x32_bf16 v[4:7], v[40:43], v[44:47], v[4:7]
	v_mfma_f32_16x16x32_bf16 v[0:3], v[36:39], v[44:47], v[0:3]
	global_load_dwordx4 v[36:39], v[30:31], off offset:2048
	global_load_dwordx4 v[40:43], v[32:33], off offset:2048
	global_load_dwordx4 v[44:47], v[34:35], off offset:1536
	s_waitcnt vmcnt(21)
	v_mfma_f32_16x16x32_bf16 v[4:7], v[52:55], v[56:59], v[4:7]
	v_mfma_f32_16x16x32_bf16 v[0:3], v[48:51], v[56:59], v[0:3]
	global_load_dwordx4 v[48:51], v[30:31], off offset:2560
	global_load_dwordx4 v[52:55], v[32:33], off offset:2560
	global_load_dwordx4 v[56:59], v[34:35], off offset:2048
	s_waitcnt vmcnt(21)
	v_mfma_f32_16x16x32_bf16 v[4:7], v[64:67], v[68:71], v[4:7]
	v_mfma_f32_16x16x32_bf16 v[0:3], v[60:63], v[68:71], v[0:3]
	global_load_dwordx4 v[60:63], v[30:31], off offset:3072
	global_load_dwordx4 v[64:67], v[32:33], off offset:3072
	global_load_dwordx4 v[68:71], v[34:35], off offset:2560
	s_waitcnt vmcnt(21)
	v_mfma_f32_16x16x32_bf16 v[4:7], v[76:79], v[80:83], v[4:7]
	v_mfma_f32_16x16x32_bf16 v[0:3], v[72:75], v[80:83], v[0:3]
	s_waitcnt vmcnt(18)
	v_mfma_f32_16x16x32_bf16 v[4:7], v[88:91], v[92:95], v[4:7]
	v_mfma_f32_16x16x32_bf16 v[0:3], v[84:87], v[92:95], v[0:3]
	s_waitcnt vmcnt(15)
	v_mfma_f32_16x16x32_bf16 v[4:7], v[100:103], v[104:107], v[4:7]
	v_mfma_f32_16x16x32_bf16 v[0:3], v[96:99], v[104:107], v[0:3]
	s_waitcnt vmcnt(12)
	v_mfma_f32_16x16x32_bf16 v[4:7], v[112:115], v[116:119], v[4:7]
	v_mfma_f32_16x16x32_bf16 v[0:3], v[108:111], v[116:119], v[0:3]
	s_waitcnt vmcnt(9)
	v_mfma_f32_16x16x32_bf16 v[4:7], v[124:127], v[128:131], v[4:7]
	v_mfma_f32_16x16x32_bf16 v[0:3], v[120:123], v[128:131], v[0:3]
	s_waitcnt vmcnt(6)
	v_mfma_f32_16x16x32_bf16 v[4:7], v[40:43], v[44:47], v[4:7]
	v_mfma_f32_16x16x32_bf16 v[0:3], v[36:39], v[44:47], v[0:3]
	s_waitcnt vmcnt(3)
	v_mfma_f32_16x16x32_bf16 v[4:7], v[52:55], v[56:59], v[4:7]
	v_mfma_f32_16x16x32_bf16 v[0:3], v[48:51], v[56:59], v[0:3]
	s_waitcnt vmcnt(0)
	v_mfma_f32_16x16x32_bf16 v[4:7], v[64:67], v[68:71], v[4:7]
	v_mfma_f32_16x16x32_bf16 v[0:3], v[60:63], v[68:71], v[0:3]
	s_nop 7

.LBB0_459:
	v_mov_b32_e32 v4, 0
	s_mov_b32 s36, -2
	v_mov_b64_e32 v[14:15], v[12:13]
	v_mov_b32_e32 v5, v4
	v_mov_b32_e32 v6, v4
	v_mov_b32_e32 v7, v4
	v_mov_b32_e32 v0, v4
	v_mov_b32_e32 v1, v4
	v_mov_b32_e32 v2, v4
	v_mov_b32_e32 v3, v4
	s_nop 1
	v_add_co_u32_e32 v16, vcc, 0x5000000, v14
	s_nop 1
	v_addc_co_u32_e32 v17, vcc, 0, v15, vcc
	v_lshl_add_u64 v[28:29], v[14:15], 0, s[40:41]
	global_load_dwordx4 v[32:35], v[16:17], off
	global_load_dwordx4 v[36:39], v[28:29], off offset:-256
	global_load_dwordx4 v[40:43], v[16:17], off offset:64
	global_load_dwordx4 v[44:47], v[28:29], off offset:-192
	global_load_dwordx4 v[48:51], v[16:17], off offset:128
	global_load_dwordx4 v[52:55], v[28:29], off offset:-128
	global_load_dwordx4 v[56:59], v[16:17], off offset:192
	global_load_dwordx4 v[60:63], v[28:29], off offset:-64
	global_load_dwordx4 v[64:67], v[16:17], off offset:256
	global_load_dwordx4 v[68:71], v[28:29], off
	global_load_dwordx4 v[72:75], v[16:17], off offset:320
	global_load_dwordx4 v[76:79], v[28:29], off offset:64
	global_load_dwordx4 v[80:83], v[16:17], off offset:384
	global_load_dwordx4 v[84:87], v[28:29], off offset:128
	global_load_dwordx4 v[88:91], v[16:17], off offset:448
	global_load_dwordx4 v[92:95], v[28:29], off offset:192
	global_load_dwordx4 v[96:99], v[16:17], off offset:512
	global_load_dwordx4 v[100:103], v[28:29], off offset:256
	global_load_dwordx4 v[104:107], v[16:17], off offset:576
	global_load_dwordx4 v[108:111], v[28:29], off offset:320
	global_load_dwordx4 v[112:115], v[16:17], off offset:640
	global_load_dwordx4 v[116:119], v[28:29], off offset:384
	global_load_dwordx4 v[120:123], v[16:17], off offset:704
	global_load_dwordx4 v[124:127], v[28:29], off offset:448
	s_waitcnt vmcnt(20)
	v_mfma_f32_16x16x32_bf16 v[0:3], v[32:35], v[36:39], v[0:3]
	v_mfma_f32_16x16x32_bf16 v[4:7], v[40:43], v[44:47], v[4:7]
	global_load_dwordx4 v[32:35], v[16:17], off offset:768
	global_load_dwordx4 v[36:39], v[28:29], off offset:512
	global_load_dwordx4 v[40:43], v[16:17], off offset:832
	global_load_dwordx4 v[44:47], v[28:29], off offset:576
	s_waitcnt vmcnt(20)
	v_mfma_f32_16x16x32_bf16 v[0:3], v[48:51], v[52:55], v[0:3]
	v_mfma_f32_16x16x32_bf16 v[4:7], v[56:59], v[60:63], v[4:7]
	global_load_dwordx4 v[48:51], v[16:17], off offset:896
	global_load_dwordx4 v[52:55], v[28:29], off offset:640
	global_load_dwordx4 v[56:59], v[16:17], off offset:960
	global_load_dwordx4 v[60:63], v[28:29], off offset:704
	s_waitcnt vmcnt(20)
	v_mfma_f32_16x16x32_bf16 v[0:3], v[64:67], v[68:71], v[0:3]
	v_mfma_f32_16x16x32_bf16 v[4:7], v[72:75], v[76:79], v[4:7]
	global_load_dwordx4 v[64:67], v[16:17], off offset:1024
	global_load_dwordx4 v[68:71], v[28:29], off offset:768
	global_load_dwordx4 v[72:75], v[16:17], off offset:1088
	global_load_dwordx4 v[76:79], v[28:29], off offset:832
	s_waitcnt vmcnt(20)
	v_mfma_f32_16x16x32_bf16 v[0:3], v[80:83], v[84:87], v[0:3]
	v_mfma_f32_16x16x32_bf16 v[4:7], v[88:91], v[92:95], v[4:7]
	global_load_dwordx4 v[80:83], v[16:17], off offset:1152
	global_load_dwordx4 v[84:87], v[28:29], off offset:896
	global_load_dwordx4 v[88:91], v[16:17], off offset:1216
	global_load_dwordx4 v[92:95], v[28:29], off offset:960
	s_waitcnt vmcnt(20)
	v_mfma_f32_16x16x32_bf16 v[0:3], v[96:99], v[100:103], v[0:3]
	v_mfma_f32_16x16x32_bf16 v[4:7], v[104:107], v[108:111], v[4:7]
	global_load_dwordx4 v[96:99], v[16:17], off offset:1280
	global_load_dwordx4 v[100:103], v[28:29], off offset:1024
	global_load_dwordx4 v[104:107], v[16:17], off offset:1344
	global_load_dwordx4 v[108:111], v[28:29], off offset:1088
	s_waitcnt vmcnt(20)
	v_mfma_f32_16x16x32_bf16 v[0:3], v[112:115], v[116:119], v[0:3]
	v_mfma_f32_16x16x32_bf16 v[4:7], v[120:123], v[124:127], v[4:7]
	global_load_dwordx4 v[112:115], v[16:17], off offset:1408
	global_load_dwordx4 v[116:119], v[28:29], off offset:1152
	global_load_dwordx4 v[120:123], v[16:17], off offset:1472
	global_load_dwordx4 v[124:127], v[28:29], off offset:1216
	s_waitcnt vmcnt(20)
	v_mfma_f32_16x16x32_bf16 v[0:3], v[32:35], v[36:39], v[0:3]
	v_mfma_f32_16x16x32_bf16 v[4:7], v[40:43], v[44:47], v[4:7]
	global_load_dwordx4 v[32:35], v[16:17], off offset:1536
	global_load_dwordx4 v[36:39], v[28:29], off offset:1280
	global_load_dwordx4 v[40:43], v[16:17], off offset:1600
	global_load_dwordx4 v[44:47], v[28:29], off offset:1344
	s_waitcnt vmcnt(20)
	v_mfma_f32_16x16x32_bf16 v[0:3], v[48:51], v[52:55], v[0:3]
	v_mfma_f32_16x16x32_bf16 v[4:7], v[56:59], v[60:63], v[4:7]
	global_load_dwordx4 v[48:51], v[16:17], off offset:1664
	global_load_dwordx4 v[52:55], v[28:29], off offset:1408
	global_load_dwordx4 v[56:59], v[16:17], off offset:1728
	global_load_dwordx4 v[60:63], v[28:29], off offset:1472
	s_waitcnt vmcnt(20)
	v_mfma_f32_16x16x32_bf16 v[0:3], v[64:67], v[68:71], v[0:3]
	v_mfma_f32_16x16x32_bf16 v[4:7], v[72:75], v[76:79], v[4:7]
	global_load_dwordx4 v[64:67], v[16:17], off offset:1792
	global_load_dwordx4 v[68:71], v[28:29], off offset:1536
	global_load_dwordx4 v[72:75], v[16:17], off offset:1856
	global_load_dwordx4 v[76:79], v[28:29], off offset:1600
	s_waitcnt vmcnt(20)
	v_mfma_f32_16x16x32_bf16 v[0:3], v[80:83], v[84:87], v[0:3]
	v_mfma_f32_16x16x32_bf16 v[4:7], v[88:91], v[92:95], v[4:7]
	global_load_dwordx4 v[80:83], v[16:17], off offset:1920
	global_load_dwordx4 v[84:87], v[28:29], off offset:1664
	global_load_dwordx4 v[88:91], v[16:17], off offset:1984
	global_load_dwordx4 v[92:95], v[28:29], off offset:1728
	s_waitcnt vmcnt(20)
	v_mfma_f32_16x16x32_bf16 v[0:3], v[96:99], v[100:103], v[0:3]
	v_mfma_f32_16x16x32_bf16 v[4:7], v[104:107], v[108:111], v[4:7]
	s_waitcnt vmcnt(16)
	v_mfma_f32_16x16x32_bf16 v[0:3], v[112:115], v[116:119], v[0:3]
	v_mfma_f32_16x16x32_bf16 v[4:7], v[120:123], v[124:127], v[4:7]
	s_waitcnt vmcnt(12)
	v_mfma_f32_16x16x32_bf16 v[0:3], v[32:35], v[36:39], v[0:3]
	v_mfma_f32_16x16x32_bf16 v[4:7], v[40:43], v[44:47], v[4:7]
	s_waitcnt vmcnt(8)
	v_mfma_f32_16x16x32_bf16 v[0:3], v[48:51], v[52:55], v[0:3]
	v_mfma_f32_16x16x32_bf16 v[4:7], v[56:59], v[60:63], v[4:7]
	s_waitcnt vmcnt(4)
	v_mfma_f32_16x16x32_bf16 v[0:3], v[64:67], v[68:71], v[0:3]
	v_mfma_f32_16x16x32_bf16 v[4:7], v[72:75], v[76:79], v[4:7]
	s_waitcnt vmcnt(0)
	v_mfma_f32_16x16x32_bf16 v[0:3], v[80:83], v[84:87], v[0:3]
	v_mfma_f32_16x16x32_bf16 v[4:7], v[88:91], v[92:95], v[4:7]
	s_nop 7
	s_ashr_i32 s39, s38, 31
	s_lshl_b64 s[28:29], s[38:39], 10
	s_add_i32 s38, s38, s90
	v_readlane_b32 s4, v250, 28
	v_readlane_b32 s5, v250, 29
	s_add_u32 s40, s40, s4
	s_addc_u32 s41, s41, s5
	v_lshl_or_b32 v14, v8, 6, s28
	v_mov_b32_e32 v15, s29
	s_cmpk_gt_i32 s38, 0x800
	v_lshl_add_u64 v[14:15], v[10:11], 0, v[14:15]
	v_pk_add_f32 v[2:3], v[2:3], v[6:7]
	v_pk_add_f32 v[0:1], v[0:1], v[4:5]
	s_nop 0
	global_store_dwordx4 v[14:15], v[0:3], off sc1
	s_nop 1
	s_cbranch_scc0 .LBB0_459
.LBB0_462:
	v_readlane_b32 s4, v251, 9
	v_readlane_b32 s5, v251, 10
	s_andn2_b64 vcc, exec, s[4:5]
	s_cbranch_vccnz .LBB0_493
	v_mov_b32_e32 v3, 0
	v_readlane_b32 s6, v250, 47
	s_cmp_gt_i32 s20, 31
	v_mov_b32_e32 v2, v3
	v_mov_b32_e32 v1, v3
	v_mov_b32_e32 v0, v3
	v_mov_b32_e32 v7, v3
	v_mov_b32_e32 v6, v3
	v_mov_b32_e32 v5, v3
	v_mov_b32_e32 v4, v3
	v_readlane_b32 s7, v250, 48
	s_cbranch_scc1 .LBB0_466
	s_lshl_b32 s28, s20, 5
	s_ashr_i32 s29, s28, 31
	s_add_i32 s36, s20, -8
	s_lshl_b64 s[28:29], s[28:29], 1
	v_readlane_b32 s4, v250, 30
	v_and_b32_e32 v0, 15, v18
	v_and_b32_e32 v1, 48, v18
	s_add_u32 s28, s4, s28
	v_readlane_b32 s4, v250, 31
	v_lshl_or_b32 v142, v0, 11, v1
	s_addc_u32 s29, s4, s29
	v_mov_b32_e32 v0, 0
	v_lshl_add_u64 v[8:9], s[28:29], 0, v[142:143]
	v_mov_b32_e32 v1, v0
	v_mov_b32_e32 v2, v0
	v_mov_b32_e32 v3, v0
	v_mov_b32_e32 v4, v0
	v_mov_b32_e32 v5, v0
	v_mov_b32_e32 v6, v0
	v_mov_b32_e32 v7, v0
	s_nop 1
	v_lshl_add_u64 v[28:29], v[8:9], 0, s[6:7]
	v_add_co_u32_e32 v30, vcc, 0xfb780000, v28
	s_nop 1
	v_addc_co_u32_e32 v31, vcc, -1, v29, vcc
	v_add_co_u32_e32 v32, vcc, 0xfb788000, v28
	s_nop 1
	v_addc_co_u32_e32 v33, vcc, -1, v29, vcc
	global_load_dwordx4 v[36:39], v[30:31], off
	global_load_dwordx4 v[40:43], v[32:33], off
	global_load_dwordx4 v[44:47], v[8:9], off
	global_load_dwordx4 v[48:51], v[30:31], off offset:512
	global_load_dwordx4 v[52:55], v[32:33], off offset:512
	global_load_dwordx4 v[56:59], v[8:9], off offset:512
	global_load_dwordx4 v[60:63], v[30:31], off offset:1024
	global_load_dwordx4 v[64:67], v[32:33], off offset:1024
	global_load_dwordx4 v[68:71], v[8:9], off offset:1024
	global_load_dwordx4 v[72:75], v[30:31], off offset:1536
	global_load_dwordx4 v[76:79], v[32:33], off offset:1536
	global_load_dwordx4 v[80:83], v[8:9], off offset:1536
	s_waitcnt vmcnt(9)
	v_mfma_f32_16x16x32_bf16 v[4:7], v[40:43], v[44:47], v[4:7]
	v_mfma_f32_16x16x32_bf16 v[0:3], v[36:39], v[44:47], v[0:3]
	s_waitcnt vmcnt(6)
	v_mfma_f32_16x16x32_bf16 v[4:7], v[52:55], v[56:59], v[4:7]
	v_mfma_f32_16x16x32_bf16 v[0:3], v[48:51], v[56:59], v[0:3]
	s_waitcnt vmcnt(3)
	v_mfma_f32_16x16x32_bf16 v[4:7], v[64:67], v[68:71], v[4:7]
	v_mfma_f32_16x16x32_bf16 v[0:3], v[60:63], v[68:71], v[0:3]
	s_waitcnt vmcnt(0)
	v_mfma_f32_16x16x32_bf16 v[4:7], v[76:79], v[80:83], v[4:7]
	v_mfma_f32_16x16x32_bf16 v[0:3], v[72:75], v[80:83], v[0:3]
	s_nop 7

.LBB0_866:
	v_readlane_b32 s6, v250, 49
	v_readlane_b32 s8, v250, 51
	v_readlane_b32 s10, v250, 34
	v_readlane_b32 s12, v250, 36
	s_and_b64 vcc, exec, s[4:5]
	v_readlane_b32 s7, v250, 50
	v_readlane_b32 s9, v250, 52
	v_readlane_b32 s11, v250, 35
	v_readlane_b32 s13, v250, 37
	v_readlane_b32 s14, v250, 53
	s_cbranch_vccz .LBB0_905
	s_cmp_eq_u32 s14, 0
	s_cbranch_scc0 .LBB0_1061
	v_readlane_b32 s4, v251, 35
	v_mov_b32_e32 v10, v222
	v_readlane_b32 s5, v251, 36
	s_andn2_b64 vcc, exec, s[4:5]
	v_readfirstlane_b32 s2, v10
	s_cbranch_vccnz .LBB0_886
	v_readlane_b32 s4, v251, 37
	v_lshlrev_b32_e32 v0, 10, v10
	v_readlane_b32 s5, v251, 38
	s_ashr_i32 s20, s2, 6
	v_and_b32_e32 v12, 63, v10
	v_and_b32_e32 v11, 0x3c00, v0
	s_mov_b64 s[38:39], -1
	s_and_b64 vcc, exec, s[4:5]
	s_cbranch_vccz .LBB0_878
	v_mov_b32_e32 v3, 0
	s_cmp_gt_i32 s20, 31
	v_mov_b32_e32 v2, v3
	v_mov_b32_e32 v1, v3
	v_mov_b32_e32 v0, v3
	v_mov_b32_e32 v7, v3
	v_mov_b32_e32 v6, v3
	v_mov_b32_e32 v5, v3
	v_mov_b32_e32 v4, v3
	s_cbranch_scc1 .LBB0_873
	s_lshl_b32 s28, s20, 5
	s_ashr_i32 s29, s28, 31
	s_add_i32 s36, s20, -8
	s_lshl_b64 s[28:29], s[28:29], 1
	v_readlane_b32 s4, v250, 30
	v_and_b32_e32 v0, 15, v10
	v_and_b32_e32 v1, 48, v10
	s_add_u32 s28, s4, s28
	v_readlane_b32 s4, v250, 31
	v_lshl_or_b32 v142, v0, 11, v1
	s_addc_u32 s29, s4, s29
	v_mov_b32_e32 v0, 0
	v_readlane_b32 s4, v251, 41
	v_lshl_add_u64 v[8:9], s[28:29], 0, v[142:143]
	v_mov_b32_e32 v1, v0
	v_mov_b32_e32 v2, v0
	v_mov_b32_e32 v3, v0
	v_mov_b32_e32 v4, v0
	v_mov_b32_e32 v5, v0
	v_mov_b32_e32 v6, v0
	v_mov_b32_e32 v7, v0
	v_readlane_b32 s5, v251, 42
	s_nop 1
	v_lshl_add_u64 v[28:29], v[8:9], 0, s[4:5]
	v_add_co_u32_e32 v28, vcc, 0xfaf80000, v28
	s_nop 1
	v_addc_co_u32_e32 v29, vcc, -1, v29, vcc
	global_load_dwordx4 v[36:39], v[28:29], off
	global_load_dwordx4 v[40:43], v[8:9], off
	global_load_dwordx4 v[44:47], v[28:29], off offset:512
	global_load_dwordx4 v[48:51], v[8:9], off offset:512
	global_load_dwordx4 v[52:55], v[28:29], off offset:1024
	global_load_dwordx4 v[56:59], v[8:9], off offset:1024
	global_load_dwordx4 v[60:63], v[28:29], off offset:1536
	global_load_dwordx4 v[64:67], v[8:9], off offset:1536
	s_waitcnt vmcnt(6)
	v_mfma_f32_16x16x32_bf16 v[0:3], v[36:39], v[40:43], v[0:3]
	v_mfma_f32_16x16x32_bf16 v[4:7], v[36:39], v[40:43], v[4:7]
	s_waitcnt vmcnt(4)
	v_mfma_f32_16x16x32_bf16 v[0:3], v[44:47], v[48:51], v[0:3]
	v_mfma_f32_16x16x32_bf16 v[4:7], v[44:47], v[48:51], v[4:7]
	s_waitcnt vmcnt(2)
	v_mfma_f32_16x16x32_bf16 v[0:3], v[52:55], v[56:59], v[0:3]
	v_mfma_f32_16x16x32_bf16 v[4:7], v[52:55], v[56:59], v[4:7]
	s_waitcnt vmcnt(0)
	v_mfma_f32_16x16x32_bf16 v[0:3], v[60:63], v[64:67], v[0:3]
	v_mfma_f32_16x16x32_bf16 v[4:7], v[60:63], v[64:67], v[4:7]
	s_nop 7

.LBB0_878:
	s_and_b64 vcc, exec, s[38:39]
	s_cbranch_vccz .LBB0_886
	v_mov_b32_e32 v3, 0
	s_cmp_gt_i32 s20, 31
	v_mov_b32_e32 v2, v3
	v_mov_b32_e32 v1, v3
	v_mov_b32_e32 v0, v3
	v_mov_b32_e32 v7, v3
	v_mov_b32_e32 v6, v3
	v_mov_b32_e32 v5, v3
	v_mov_b32_e32 v4, v3
	s_cbranch_scc1 .LBB0_882
	s_lshl_b32 s28, s20, 5
	s_ashr_i32 s29, s28, 31
	s_add_i32 s36, s20, -8
	s_lshl_b64 s[28:29], s[28:29], 1
	v_and_b32_e32 v0, 15, v10
	v_and_b32_e32 v1, 48, v10
	s_add_u32 s28, s66, s28
	v_lshl_or_b32 v142, v0, 11, v1
	s_addc_u32 s29, s67, s29
	v_mov_b32_e32 v0, 0
	v_lshl_add_u64 v[8:9], s[28:29], 0, v[142:143]
	v_mov_b32_e32 v1, v0
	v_mov_b32_e32 v2, v0
	v_mov_b32_e32 v3, v0
	v_mov_b32_e32 v4, v0
	v_mov_b32_e32 v5, v0
	v_mov_b32_e32 v6, v0
	v_mov_b32_e32 v7, v0
	s_nop 1
	v_lshl_add_u64 v[28:29], v[8:9], 0, s[12:13]
	v_lshl_add_u64 v[30:31], v[8:9], 0, s[10:11]
	v_add_co_u32_e32 v32, vcc, 0x9280000, v8
	s_nop 1
	v_addc_co_u32_e32 v33, vcc, 0, v9, vcc
	global_load_dwordx4 v[36:39], v[32:33], off
	global_load_dwordx4 v[40:43], v[28:29], off
	global_load_dwordx4 v[44:47], v[30:31], off
	global_load_dwordx4 v[48:51], v[32:33], off offset:512
	global_load_dwordx4 v[52:55], v[28:29], off offset:512
	global_load_dwordx4 v[56:59], v[30:31], off offset:512
	global_load_dwordx4 v[60:63], v[32:33], off offset:1024
	global_load_dwordx4 v[64:67], v[28:29], off offset:1024
	global_load_dwordx4 v[68:71], v[30:31], off offset:1024
	global_load_dwordx4 v[72:75], v[32:33], off offset:1536
	global_load_dwordx4 v[76:79], v[28:29], off offset:1536
	global_load_dwordx4 v[80:83], v[30:31], off offset:1536
	s_waitcnt vmcnt(9)
	v_mfma_f32_16x16x32_bf16 v[4:7], v[40:43], v[36:39], v[4:7]
	v_mfma_f32_16x16x32_bf16 v[0:3], v[44:47], v[36:39], v[0:3]
	s_waitcnt vmcnt(6)
	v_mfma_f32_16x16x32_bf16 v[4:7], v[52:55], v[48:51], v[4:7]
	v_mfma_f32_16x16x32_bf16 v[0:3], v[56:59], v[48:51], v[0:3]
	s_waitcnt vmcnt(3)
	v_mfma_f32_16x16x32_bf16 v[4:7], v[64:67], v[60:63], v[4:7]
	v_mfma_f32_16x16x32_bf16 v[0:3], v[68:71], v[60:63], v[0:3]
	s_waitcnt vmcnt(0)
	v_mfma_f32_16x16x32_bf16 v[4:7], v[76:79], v[72:75], v[4:7]
	v_mfma_f32_16x16x32_bf16 v[0:3], v[80:83], v[72:75], v[0:3]
	s_nop 7

.LBB0_1062:
	v_readlane_b32 s2, v250, 56
	s_lshl_b32 s38, s2, 10
	s_add_i32 s28, s38, 0xfffffc00
	s_ashr_i32 s29, s28, 31
	v_readlane_b32 s44, v252, 18
	s_lshl_b64 s[28:29], s[28:29], 2
	v_readlane_b32 s48, v252, 22
	v_readlane_b32 s45, v252, 19
	v_readlane_b32 s49, v252, 23
	s_add_u32 s44, s48, s28
	v_readlane_b32 s46, v252, 20
	v_readlane_b32 s50, v252, 24
	s_addc_u32 s45, s49, s29
	v_readlane_b32 s4, v250, 1
	v_readlane_b32 s47, v252, 21
	v_readlane_b32 s51, v252, 25
	s_add_u32 s46, s50, s28
	v_mov_b32_e32 v12, v222
	v_readlane_b32 s5, v250, 2
	v_readlane_b32 s10, v250, 54
	s_waitcnt lgkmcnt(0)
	s_addc_u32 s47, s51, s29
	s_andn2_b64 vcc, exec, s[4:5]
	v_readfirstlane_b32 s2, v12
	v_readlane_b32 s11, v250, 55
	v_readlane_b32 s52, v252, 26
	v_readlane_b32 s53, v252, 27
	v_readlane_b32 s54, v252, 28
	v_readlane_b32 s55, v252, 29
	v_readlane_b32 s56, v252, 30
	v_readlane_b32 s57, v252, 31
	v_readlane_b32 s58, v252, 32
	v_readlane_b32 s59, v252, 33
	s_cbranch_vccnz .LBB0_1070
	s_ashr_i32 s20, s2, 6
	v_mov_b32_e32 v3, 0
	s_cmp_gt_i32 s20, 31
	v_and_b32_e32 v13, 15, v12
	v_mov_b32_e32 v2, v3
	v_mov_b32_e32 v1, v3
	v_mov_b32_e32 v0, v3
	v_mov_b32_e32 v7, v3
	v_mov_b32_e32 v6, v3
	v_mov_b32_e32 v5, v3
	v_mov_b32_e32 v4, v3
	s_cbranch_scc1 .LBB0_1066
	v_and_b32_e32 v0, 48, v12
	s_lshl_b32 s28, s20, 5
	v_lshl_or_b32 v142, v13, 11, v0
	s_ashr_i32 s29, s28, 31
	v_lshl_add_u64 v[0:1], s[28:29], 1, v[142:143]
	s_add_i32 s36, s20, -8
	v_lshl_add_u64 v[2:3], s[42:43], 0, v[0:1]
	s_mov_b64 s[28:29], 0x4000000
	v_readlane_b32 s4, v250, 38
	v_lshl_add_u64 v[8:9], v[2:3], 0, s[28:29]
	v_readlane_b32 s5, v250, 39
	s_add_u32 s28, s40, s4
	s_addc_u32 s29, s41, s5
	v_lshl_add_u64 v[10:11], s[28:29], 0, v[0:1]
	v_mov_b32_e32 v0, 0
	v_mov_b32_e32 v1, v0
	v_mov_b32_e32 v2, v0
	v_mov_b32_e32 v3, v0
	v_mov_b32_e32 v4, v0
	v_mov_b32_e32 v5, v0
	v_mov_b32_e32 v6, v0
	v_mov_b32_e32 v7, v0
	s_nop 1
	v_add_co_u32_e32 v28, vcc, 0x8000, v10
	s_nop 1
	v_addc_co_u32_e32 v29, vcc, 0, v11, vcc
	global_load_dwordx4 v[36:39], v[10:11], off
	global_load_dwordx4 v[40:43], v[8:9], off
	global_load_dwordx4 v[44:47], v[28:29], off
	global_load_dwordx4 v[48:51], v[10:11], off offset:512
	global_load_dwordx4 v[52:55], v[8:9], off offset:512
	global_load_dwordx4 v[56:59], v[28:29], off offset:512
	global_load_dwordx4 v[60:63], v[10:11], off offset:1024
	global_load_dwordx4 v[64:67], v[8:9], off offset:1024
	global_load_dwordx4 v[68:71], v[28:29], off offset:1024
	global_load_dwordx4 v[72:75], v[10:11], off offset:1536
	global_load_dwordx4 v[76:79], v[8:9], off offset:1536
	global_load_dwordx4 v[80:83], v[28:29], off offset:1536
	s_waitcnt vmcnt(9)
	v_mfma_f32_16x16x32_bf16 v[0:3], v[36:39], v[40:43], v[0:3]
	v_mfma_f32_16x16x32_bf16 v[4:7], v[44:47], v[40:43], v[4:7]
	s_waitcnt vmcnt(6)
	v_mfma_f32_16x16x32_bf16 v[0:3], v[48:51], v[52:55], v[0:3]
	v_mfma_f32_16x16x32_bf16 v[4:7], v[56:59], v[52:55], v[4:7]
	s_waitcnt vmcnt(3)
	v_mfma_f32_16x16x32_bf16 v[0:3], v[60:63], v[64:67], v[0:3]
	v_mfma_f32_16x16x32_bf16 v[4:7], v[68:71], v[64:67], v[4:7]
	s_waitcnt vmcnt(0)
	v_mfma_f32_16x16x32_bf16 v[0:3], v[72:75], v[76:79], v[0:3]
	v_mfma_f32_16x16x32_bf16 v[4:7], v[80:83], v[76:79], v[4:7]
	s_nop 7
